# scan chunk loop: head set-up (addresses, decay readlane) rotated to the tail of the previous step, in front of its closing wait and barrier
# speedup vs baseline: 1.0039x; 1.0015x over previous
.LBB0_377:
	s_or_b64 exec, exec, s[76:77]
	s_waitcnt lgkmcnt(0)
	s_barrier
	s_ashr_i32 s79, s78, 31
	s_mov_b64 s[76:77], -1
	s_and_b64 vcc, exec, s[6:7]
	s_cbranch_vccz .LBB0_381
	s_waitcnt vmcnt(16)
	v_mov_b32_e32 v242, 0x3020706
	v_mov_b32_e32 v243, 0x5040100
	v_cndmask_b32_e64 v242, v242, v243, s[40:41]
	s_ashr_i32 s76, s26, 2
	s_lshl_b32 s4, s24, 1
	s_ashr_i32 s77, s76, 31
	s_and_b32 s4, s4, 0x300
	s_lshl_b64 s[76:77], s[76:77], 21
	s_or_b32 s4, s76, s4
	s_add_u32 s27, s17, s4
	v_mov_b32_e32 v32, 0
	s_addc_u32 s28, s20, s77
	s_mov_b32 s29, 0
	s_mov_b64 s[78:79], 0
	v_mov_b32_e32 v33, v32
	v_mov_b32_e32 v34, v32
	v_mov_b32_e32 v35, v32
	v_mov_b32_e32 v36, v32
	v_mov_b32_e32 v37, v32
	v_mov_b32_e32 v38, v32
	v_mov_b32_e32 v39, v32
	v_mov_b32_e32 v40, v32
	v_mov_b32_e32 v41, v32
	v_mov_b32_e32 v42, v32
	v_mov_b32_e32 v43, v32
	v_mov_b32_e32 v44, v32
	v_mov_b32_e32 v45, v32
	v_mov_b32_e32 v46, v32
	v_mov_b32_e32 v47, v32
	v_mov_b32_e32 v48, v32
	v_mov_b32_e32 v49, v32
	v_mov_b32_e32 v50, v32
	v_mov_b32_e32 v51, v32
	s_waitcnt vmcnt(5)
	v_mov_b32_e32 v52, v32
	v_mov_b32_e32 v53, v32
	v_mov_b32_e32 v54, v32
	v_mov_b32_e32 v55, v32
	v_mov_b32_e32 v56, v32
	v_mov_b32_e32 v57, v32
	v_mov_b32_e32 v58, v32
	v_mov_b32_e32 v59, v32
	v_mov_b32_e32 v60, v32
	v_mov_b32_e32 v61, v32
	v_mov_b32_e32 v62, v32
	v_mov_b32_e32 v63, v32
	v_mov_b32_e32 v64, v32
	v_mov_b32_e32 v65, v32
	v_mov_b32_e32 v66, v32
	v_mov_b32_e32 v67, v32
	v_mov_b32_e32 v68, v32
	v_mov_b32_e32 v69, v32
	v_mov_b32_e32 v70, v32
	v_mov_b32_e32 v71, v32
	v_mov_b32_e32 v72, v32
	v_mov_b32_e32 v73, v32
	v_mov_b32_e32 v74, v32
	v_mov_b32_e32 v75, v32
	v_mov_b32_e32 v76, v32
	v_mov_b32_e32 v77, v32
	v_mov_b32_e32 v78, v32
	v_mov_b32_e32 v79, v32
	v_mov_b32_e32 v80, v32
	v_mov_b32_e32 v81, v32
	v_mov_b32_e32 v82, v32
	v_mov_b32_e32 v83, v32
	v_mov_b32_e32 v84, v32
	v_mov_b32_e32 v85, v32
	v_mov_b32_e32 v86, v32
	v_mov_b32_e32 v87, v32
	v_mov_b32_e32 v88, v32
	v_mov_b32_e32 v89, v32
	v_mov_b32_e32 v90, v32
	v_mov_b32_e32 v91, v32
	v_mov_b32_e32 v92, v32
	v_mov_b32_e32 v93, v32
	v_mov_b32_e32 v94, v32
	v_mov_b32_e32 v95, v32
	s_waitcnt vmcnt(0)
	s_bitcmp1_b32 s29, 0
	s_cselect_b32 s34, 0xf400, 0
	s_add_i32 s30, s22, s29
	s_ashr_i32 s31, s30, 31
	s_lshl_b64 s[30:31], s[30:31], 14
	v_lshl_add_u64 v[240:241], v[214:215], 0, s[30:31]
	v_add_u32_e32 v194, s34, v235
	v_readlane_b32 s4, v164, s29
	s_add_i32 s29, s29, 1
	v_add_u32_e32 v165, v194, v236
	v_add_u32_e32 v194, v194, v244
	v_add_u32_e32 v195, v194, v236
.LBB0_379:
	ds_read_b128 v[96:99], v165
	ds_read_b128 v[166:169], v165 offset:32
	ds_read_b128 v[100:103], v165 offset:8704
	ds_read_b128 v[170:173], v165 offset:8736
	ds_read_b128 v[104:107], v165 offset:17408
	ds_read_b128 v[174:177], v165 offset:17440
	ds_read_b128 v[108:111], v165 offset:26112
	ds_read_b128 v[178:181], v165 offset:26144
	v_cvt_pk_bf16_f32 v182, v80, v81
	v_cvt_pk_bf16_f32 v183, v82, v83
	v_cvt_pk_bf16_f32 v184, v84, v85
	v_cvt_pk_bf16_f32 v185, v86, v87
	s_waitcnt vmcnt(16)
	v_and_b32_e32 v31, 0xffff0000, v15
	v_lshlrev_b32_e32 v30, 16, v15
	v_and_b32_e32 v29, 0xffff0000, v14
	v_lshlrev_b32_e32 v28, 16, v14
	v_and_b32_e32 v27, 0xffff0000, v13
	v_lshlrev_b32_e32 v26, 16, v13
	v_and_b32_e32 v25, 0xffff0000, v12
	v_lshlrev_b32_e32 v24, 16, v12
	v_and_b32_e32 v23, 0xffff0000, v11
	v_lshlrev_b32_e32 v22, 16, v11
	v_and_b32_e32 v21, 0xffff0000, v10
	v_lshlrev_b32_e32 v20, 16, v10
	v_and_b32_e32 v19, 0xffff0000, v9
	v_lshlrev_b32_e32 v18, 16, v9
	v_and_b32_e32 v17, 0xffff0000, v8
	v_lshlrev_b32_e32 v16, 16, v8
	v_and_b32_e32 v15, 0xffff0000, v7
	v_lshlrev_b32_e32 v14, 16, v7
	v_and_b32_e32 v13, 0xffff0000, v6
	v_lshlrev_b32_e32 v12, 16, v6
	v_and_b32_e32 v11, 0xffff0000, v5
	v_lshlrev_b32_e32 v10, 16, v5
	v_and_b32_e32 v9, 0xffff0000, v4
	v_lshlrev_b32_e32 v8, 16, v4
	v_and_b32_e32 v7, 0xffff0000, v3
	v_lshlrev_b32_e32 v6, 16, v3
	v_and_b32_e32 v5, 0xffff0000, v2
	v_lshlrev_b32_e32 v4, 16, v2
	v_and_b32_e32 v3, 0xffff0000, v1
	v_lshlrev_b32_e32 v2, 16, v1
	v_and_b32_e32 v1, 0xffff0000, v0
	v_lshlrev_b32_e32 v0, 16, v0
	s_waitcnt lgkmcnt(7)
	s_nop 0
	v_mfma_f32_32x32x16_bf16 v[128:143], v[96:99], v[182:185], v[0:15]
	s_waitcnt lgkmcnt(5)
	v_mfma_f32_32x32x16_bf16 v[144:159], v[100:103], v[182:185], v[16:31]
	s_waitcnt lgkmcnt(3)
	v_mfma_f32_32x32x16_bf16 v[112:127], v[104:107], v[182:185], 0
	s_waitcnt lgkmcnt(1)
	v_mfma_f32_32x32x16_bf16 v[96:111], v[108:111], v[182:185], 0
	global_load_dwordx4 v[0:3], v[240:241], off
	global_load_dwordx4 v[4:7], v[240:241], off offset:1024
	global_load_dwordx4 v[8:11], v[240:241], off offset:2048
	global_load_dwordx4 v[12:15], v[240:241], off offset:3072
	ds_read_b128 v[182:185], v165 offset:26176
	ds_read_b128 v[186:189], v165 offset:17472
	ds_read_b128 v[190:193], v165 offset:8768
	ds_read_b128 v[220:223], v165 offset:64
	v_cvt_pk_bf16_f32 v246, v88, v89
	v_cvt_pk_bf16_f32 v247, v90, v91
	v_cvt_pk_bf16_f32 v248, v92, v93
	v_cvt_pk_bf16_f32 v249, v94, v95
	s_nop 1
	v_mfma_f32_32x32x16_bf16 v[128:143], v[166:169], v[246:249], v[128:143]
	v_mfma_f32_32x32x16_bf16 v[144:159], v[170:173], v[246:249], v[144:159]
	v_mfma_f32_32x32x16_bf16 v[112:127], v[174:177], v[246:249], v[112:127]
	s_waitcnt lgkmcnt(4)
	v_mfma_f32_32x32x16_bf16 v[96:111], v[178:181], v[246:249], v[96:111]
	ds_read_b128 v[166:169], v165 offset:96
	ds_read_b128 v[170:173], v165 offset:8800
	ds_read_b128 v[174:177], v165 offset:17504
	ds_read_b128 v[178:181], v165 offset:26208
	v_cvt_pk_bf16_f32 v246, v64, v65
	v_cvt_pk_bf16_f32 v247, v66, v67
	v_cvt_pk_bf16_f32 v248, v68, v69
	v_cvt_pk_bf16_f32 v249, v70, v71
	s_waitcnt lgkmcnt(4)
	s_nop 0
	v_mfma_f32_32x32x16_bf16 v[128:143], v[220:223], v[246:249], v[128:143]
	v_mfma_f32_32x32x16_bf16 v[144:159], v[190:193], v[246:249], v[144:159]
	v_mfma_f32_32x32x16_bf16 v[112:127], v[186:189], v[246:249], v[112:127]
	v_mfma_f32_32x32x16_bf16 v[96:111], v[182:185], v[246:249], v[96:111]
	ds_read_b128 v[182:185], v165 offset:26240
	ds_read_b128 v[186:189], v165 offset:17536
	ds_read_b128 v[190:193], v165 offset:8832
	ds_read_b128 v[220:223], v165 offset:128
	v_cvt_pk_bf16_f32 v246, v72, v73
	v_cvt_pk_bf16_f32 v247, v74, v75
	v_cvt_pk_bf16_f32 v248, v76, v77
	v_cvt_pk_bf16_f32 v249, v78, v79
	s_waitcnt lgkmcnt(7)
	s_nop 0
	v_mfma_f32_32x32x16_bf16 v[128:143], v[166:169], v[246:249], v[128:143]
	s_waitcnt lgkmcnt(6)
	v_mfma_f32_32x32x16_bf16 v[144:159], v[170:173], v[246:249], v[144:159]
	s_waitcnt lgkmcnt(5)
	v_mfma_f32_32x32x16_bf16 v[112:127], v[174:177], v[246:249], v[112:127]
	s_waitcnt lgkmcnt(4)
	v_mfma_f32_32x32x16_bf16 v[96:111], v[178:181], v[246:249], v[96:111]
	ds_read_b128 v[166:169], v165 offset:160
	ds_read_b128 v[170:173], v165 offset:8864
	ds_read_b128 v[174:177], v165 offset:17568
	ds_read_b128 v[178:181], v165 offset:26272
	v_cvt_pk_bf16_f32 v246, v48, v49
	v_cvt_pk_bf16_f32 v247, v50, v51
	v_cvt_pk_bf16_f32 v248, v52, v53
	v_cvt_pk_bf16_f32 v249, v54, v55
	s_waitcnt lgkmcnt(4)
	s_nop 0
	v_mfma_f32_32x32x16_bf16 v[128:143], v[220:223], v[246:249], v[128:143]
	v_mfma_f32_32x32x16_bf16 v[144:159], v[190:193], v[246:249], v[144:159]
	v_mfma_f32_32x32x16_bf16 v[112:127], v[186:189], v[246:249], v[112:127]
	v_mfma_f32_32x32x16_bf16 v[96:111], v[182:185], v[246:249], v[96:111]
	ds_read_b128 v[182:185], v165 offset:26304
	ds_read_b128 v[186:189], v165 offset:17600
	ds_read_b128 v[190:193], v165 offset:8896
	ds_read_b128 v[220:223], v165 offset:192
	v_cvt_pk_bf16_f32 v246, v56, v57
	v_cvt_pk_bf16_f32 v247, v58, v59
	v_cvt_pk_bf16_f32 v248, v60, v61
	v_cvt_pk_bf16_f32 v249, v62, v63
	s_waitcnt lgkmcnt(7)
	s_nop 0
	v_mfma_f32_32x32x16_bf16 v[128:143], v[166:169], v[246:249], v[128:143]
	s_waitcnt lgkmcnt(6)
	v_mfma_f32_32x32x16_bf16 v[144:159], v[170:173], v[246:249], v[144:159]
	s_waitcnt lgkmcnt(5)
	v_mfma_f32_32x32x16_bf16 v[112:127], v[174:177], v[246:249], v[112:127]
	s_waitcnt lgkmcnt(4)
	v_mfma_f32_32x32x16_bf16 v[96:111], v[178:181], v[246:249], v[96:111]
	ds_read_b128 v[166:169], v165 offset:224
	ds_read_b128 v[170:173], v165 offset:8928
	ds_read_b128 v[174:177], v165 offset:17632
	ds_read_b128 v[178:181], v165 offset:26336
	v_cvt_pk_bf16_f32 v246, v32, v33
	v_cvt_pk_bf16_f32 v247, v34, v35
	v_cvt_pk_bf16_f32 v248, v36, v37
	v_cvt_pk_bf16_f32 v249, v38, v39
	s_waitcnt lgkmcnt(4)
	s_nop 0
	v_mfma_f32_32x32x16_bf16 v[128:143], v[220:223], v[246:249], v[128:143]
	v_mfma_f32_32x32x16_bf16 v[144:159], v[190:193], v[246:249], v[144:159]
	v_mfma_f32_32x32x16_bf16 v[112:127], v[186:189], v[246:249], v[112:127]
	v_mfma_f32_32x32x16_bf16 v[96:111], v[182:185], v[246:249], v[96:111]
	ds_read_b128 v[182:185], v195 offset:57952
	ds_read_b128 v[186:189], v195 offset:57920
	ds_read_b128 v[190:193], v195 offset:57888
	ds_read_b128 v[220:223], v195 offset:57856
	ds_read_b128 v[246:249], v195 offset:53248
	ds_read_b128 v[250:253], v195 offset:53280
	v_cvt_pk_bf16_f32 v204, v40, v41
	v_cvt_pk_bf16_f32 v205, v42, v43
	v_cvt_pk_bf16_f32 v206, v44, v45
	v_cvt_pk_bf16_f32 v207, v46, v47
	s_waitcnt lgkmcnt(9)
	s_nop 0
	v_mfma_f32_32x32x16_bf16 v[128:143], v[166:169], v[204:207], v[128:143]
	s_waitcnt lgkmcnt(8)
	v_mfma_f32_32x32x16_bf16 v[144:159], v[170:173], v[204:207], v[144:159]
	s_waitcnt lgkmcnt(7)
	v_mfma_f32_32x32x16_bf16 v[112:127], v[174:177], v[204:207], v[112:127]
	s_waitcnt lgkmcnt(6)
	v_mfma_f32_32x32x16_bf16 v[96:111], v[178:181], v[204:207], v[96:111]
	v_add_u32_e32 v165, v194, v196
	s_nop 4
	v_cvt_pk_bf16_f32 v128, v128, v129
	v_cvt_pk_bf16_f32 v129, v130, v131
	v_cvt_pk_bf16_f32 v130, v132, v133
	v_cvt_pk_bf16_f32 v131, v134, v135
	v_cvt_pk_bf16_f32 v132, v136, v137
	v_cvt_pk_bf16_f32 v133, v138, v139
	v_cvt_pk_bf16_f32 v134, v140, v141
	v_cvt_pk_bf16_f32 v135, v142, v143
	v_cvt_pk_bf16_f32 v136, v144, v145
	v_cvt_pk_bf16_f32 v137, v146, v147
	v_cvt_pk_bf16_f32 v138, v148, v149
	v_cvt_pk_bf16_f32 v139, v150, v151
	v_cvt_pk_bf16_f32 v140, v152, v153
	v_cvt_pk_bf16_f32 v141, v154, v155
	v_cvt_pk_bf16_f32 v142, v156, v157
	v_cvt_pk_bf16_f32 v143, v158, v159
	ds_read_b128 v[144:147], v165 offset:34816
	ds_read_b128 v[148:151], v165 offset:34848
	ds_read_b128 v[152:155], v165 offset:34880
	ds_read_b128 v[156:159], v165 offset:34912
	s_waitcnt lgkmcnt(6)
	v_mfma_f32_32x32x16_bf16 v[96:111], v[220:223], v[128:131], v[96:111]
	v_mfma_f32_32x32x16_bf16 v[96:111], v[190:193], v[132:135], v[96:111]
	s_waitcnt lgkmcnt(5)
	v_mfma_f32_32x32x16_bf16 v[112:127], v[246:249], v[128:131], v[112:127]
	v_mfma_f32_32x32x16_bf16 v[96:111], v[186:189], v[136:139], v[96:111]
	s_waitcnt lgkmcnt(4)
	v_mfma_f32_32x32x16_bf16 v[112:127], v[250:253], v[132:135], v[112:127]
	v_mfma_f32_32x32x16_bf16 v[96:111], v[182:185], v[140:143], v[96:111]
	ds_read_b128 v[166:169], v165 offset:39424
	ds_read_b128 v[170:173], v165 offset:39456
	ds_read_b128 v[174:177], v165 offset:39520
	ds_read_b128 v[178:181], v165 offset:39488
	v_mul_f32_e64 v94, v94, s4
	v_mul_f32_e64 v95, v95, s4
	v_pk_mul_f32 v[92:93], v[92:93], s[4:5] op_sel_hi:[1,0]
	v_pk_mul_f32 v[90:91], v[90:91], s[4:5] op_sel_hi:[1,0]
	v_pk_mul_f32 v[88:89], v[88:89], s[4:5] op_sel_hi:[1,0]
	v_pk_mul_f32 v[86:87], v[86:87], s[4:5] op_sel_hi:[1,0]
	v_pk_mul_f32 v[84:85], v[84:85], s[4:5] op_sel_hi:[1,0]
	v_pk_mul_f32 v[82:83], v[82:83], s[4:5] op_sel_hi:[1,0]
	v_pk_mul_f32 v[80:81], v[80:81], s[4:5] op_sel_hi:[1,0]
	s_waitcnt lgkmcnt(7)
	s_nop 0
	v_mfma_f32_32x32x16_bf16 v[80:95], v[144:147], v[128:131], v[80:95]
	s_add_u32 s80, s27, s78
	s_addc_u32 s81, s28, s79
	v_cvt_pk_bf16_f32 v182, v112, v113
	v_cvt_pk_bf16_f32 v183, v114, v115
	v_cvt_pk_bf16_f32 v184, v116, v117
	v_cvt_pk_bf16_f32 v185, v118, v119
	s_waitcnt lgkmcnt(6)
	v_mfma_f32_32x32x16_bf16 v[80:95], v[148:151], v[132:135], v[80:95]
	v_cvt_pk_bf16_f32 v186, v120, v121
	v_cvt_pk_bf16_f32 v187, v122, v123
	v_cvt_pk_bf16_f32 v188, v124, v125
	v_cvt_pk_bf16_f32 v189, v126, v127
	s_waitcnt lgkmcnt(5)
	v_mfma_f32_32x32x16_bf16 v[80:95], v[152:155], v[136:139], v[80:95]
	v_mov_b32_dpp v190, v182 quad_perm:[1,0,3,2] row_mask:0xf bank_mask:0xf
	v_mov_b32_dpp v191, v183 quad_perm:[1,0,3,2] row_mask:0xf bank_mask:0xf
	v_mov_b32_dpp v192, v184 quad_perm:[1,0,3,2] row_mask:0xf bank_mask:0xf
	v_mov_b32_dpp v193, v185 quad_perm:[1,0,3,2] row_mask:0xf bank_mask:0xf
	v_add_u32_e32 v246, 0x2000, v213
	s_waitcnt lgkmcnt(4)
	v_mfma_f32_32x32x16_bf16 v[80:95], v[156:159], v[140:143], v[80:95]
	v_mov_b32_dpp v220, v186 quad_perm:[1,0,3,2] row_mask:0xf bank_mask:0xf
	v_mov_b32_dpp v221, v187 quad_perm:[1,0,3,2] row_mask:0xf bank_mask:0xf
	v_mov_b32_dpp v222, v188 quad_perm:[1,0,3,2] row_mask:0xf bank_mask:0xf
	v_mov_b32_dpp v223, v189 quad_perm:[1,0,3,2] row_mask:0xf bank_mask:0xf
	v_add_u32_e32 v247, 0x4000, v213
	ds_read_b128 v[144:147], v165 offset:44096
	ds_read_b128 v[148:151], v165 offset:44128
	ds_read_b128 v[152:155], v165 offset:44032
	ds_read_b128 v[156:159], v165 offset:44064
	v_mul_f32_e64 v78, v78, s4
	v_mul_f32_e64 v79, v79, s4
	v_pk_mul_f32 v[76:77], v[76:77], s[4:5] op_sel_hi:[1,0]
	v_pk_mul_f32 v[74:75], v[74:75], s[4:5] op_sel_hi:[1,0]
	v_pk_mul_f32 v[72:73], v[72:73], s[4:5] op_sel_hi:[1,0]
	v_pk_mul_f32 v[70:71], v[70:71], s[4:5] op_sel_hi:[1,0]
	v_pk_mul_f32 v[68:69], v[68:69], s[4:5] op_sel_hi:[1,0]
	v_pk_mul_f32 v[66:67], v[66:67], s[4:5] op_sel_hi:[1,0]
	v_pk_mul_f32 v[64:65], v[64:65], s[4:5] op_sel_hi:[1,0]
	s_waitcnt lgkmcnt(6)
	s_nop 0
	v_mfma_f32_32x32x16_bf16 v[64:79], v[170:173], v[128:131], v[64:79]
	v_perm_b32 v182, v190, v182, v242
	v_perm_b32 v183, v191, v183, v242
	v_perm_b32 v184, v192, v184, v242
	v_perm_b32 v185, v193, v185, v242
	v_add_u32_e32 v248, 0x6000, v213
	v_mfma_f32_32x32x16_bf16 v[64:79], v[166:169], v[132:135], v[64:79]
	v_perm_b32 v186, v220, v186, v242
	v_perm_b32 v187, v221, v187, v242
	v_perm_b32 v188, v222, v188, v242
	v_perm_b32 v189, v223, v189, v242
	s_waitcnt lgkmcnt(5)
	v_mfma_f32_32x32x16_bf16 v[64:79], v[174:177], v[136:139], v[64:79]
	global_store_dword v213, v182, s[80:81]
	global_store_dword v213, v183, s[80:81] offset:2048
	global_store_dword v246, v184, s[80:81]
	global_store_dword v246, v185, s[80:81] offset:2048
	s_waitcnt lgkmcnt(4)
	v_mfma_f32_32x32x16_bf16 v[64:79], v[178:181], v[140:143], v[64:79]
	global_store_dword v247, v186, s[80:81]
	global_store_dword v247, v187, s[80:81] offset:2048
	global_store_dword v248, v188, s[80:81]
	global_store_dword v248, v189, s[80:81] offset:2048
	ds_read_b128 v[166:169], v165 offset:48736
	ds_read_b128 v[170:173], v165 offset:48704
	ds_read_b128 v[174:177], v165 offset:48640
	ds_read_b128 v[178:181], v165 offset:48672
	v_mul_f32_e64 v62, v62, s4
	v_mul_f32_e64 v63, v63, s4
	v_pk_mul_f32 v[60:61], v[60:61], s[4:5] op_sel_hi:[1,0]
	v_pk_mul_f32 v[58:59], v[58:59], s[4:5] op_sel_hi:[1,0]
	v_pk_mul_f32 v[56:57], v[56:57], s[4:5] op_sel_hi:[1,0]
	v_pk_mul_f32 v[54:55], v[54:55], s[4:5] op_sel_hi:[1,0]
	v_pk_mul_f32 v[52:53], v[52:53], s[4:5] op_sel_hi:[1,0]
	v_pk_mul_f32 v[50:51], v[50:51], s[4:5] op_sel_hi:[1,0]
	v_pk_mul_f32 v[48:49], v[48:49], s[4:5] op_sel_hi:[1,0]
	s_waitcnt lgkmcnt(7)
	s_nop 0
	v_mfma_f32_32x32x16_bf16 v[48:63], v[144:147], v[128:131], v[48:63]
	v_cvt_pk_bf16_f32 v182, v96, v97
	v_cvt_pk_bf16_f32 v183, v98, v99
	v_cvt_pk_bf16_f32 v184, v100, v101
	v_cvt_pk_bf16_f32 v185, v102, v103
	s_waitcnt lgkmcnt(6)
	v_mfma_f32_32x32x16_bf16 v[48:63], v[148:151], v[132:135], v[48:63]
	v_cvt_pk_bf16_f32 v186, v104, v105
	v_cvt_pk_bf16_f32 v187, v106, v107
	v_cvt_pk_bf16_f32 v188, v108, v109
	v_cvt_pk_bf16_f32 v189, v110, v111
	s_waitcnt lgkmcnt(5)
	v_mfma_f32_32x32x16_bf16 v[48:63], v[152:155], v[136:139], v[48:63]
	v_mov_b32_dpp v190, v182 quad_perm:[1,0,3,2] row_mask:0xf bank_mask:0xf
	v_mov_b32_dpp v191, v183 quad_perm:[1,0,3,2] row_mask:0xf bank_mask:0xf
	v_mov_b32_dpp v192, v184 quad_perm:[1,0,3,2] row_mask:0xf bank_mask:0xf
	v_mov_b32_dpp v193, v185 quad_perm:[1,0,3,2] row_mask:0xf bank_mask:0xf
	v_add_u32_e32 v246, 0x8000, v213
	s_waitcnt lgkmcnt(4)
	v_mfma_f32_32x32x16_bf16 v[48:63], v[156:159], v[140:143], v[48:63]
	v_mov_b32_dpp v220, v186 quad_perm:[1,0,3,2] row_mask:0xf bank_mask:0xf
	v_mov_b32_dpp v221, v187 quad_perm:[1,0,3,2] row_mask:0xf bank_mask:0xf
	v_mov_b32_dpp v222, v188 quad_perm:[1,0,3,2] row_mask:0xf bank_mask:0xf
	v_mov_b32_dpp v223, v189 quad_perm:[1,0,3,2] row_mask:0xf bank_mask:0xf
	v_add_u32_e32 v247, 0xa000, v213
	v_pk_mul_f32 v[46:47], v[46:47], s[4:5] op_sel_hi:[1,0]
	v_pk_mul_f32 v[44:45], v[44:45], s[4:5] op_sel_hi:[1,0]
	v_pk_mul_f32 v[42:43], v[42:43], s[4:5] op_sel_hi:[1,0]
	v_pk_mul_f32 v[40:41], v[40:41], s[4:5] op_sel_hi:[1,0]
	v_pk_mul_f32 v[38:39], v[38:39], s[4:5] op_sel_hi:[1,0]
	v_pk_mul_f32 v[36:37], v[36:37], s[4:5] op_sel_hi:[1,0]
	v_pk_mul_f32 v[34:35], v[34:35], s[4:5] op_sel_hi:[1,0]
	v_pk_mul_f32 v[32:33], v[32:33], s[4:5] op_sel_hi:[1,0]
	s_waitcnt lgkmcnt(3)
	s_nop 0
	v_mfma_f32_32x32x16_bf16 v[32:47], v[166:169], v[128:131], v[32:47]
	v_perm_b32 v182, v190, v182, v242
	v_perm_b32 v183, v191, v183, v242
	v_perm_b32 v184, v192, v184, v242
	v_perm_b32 v185, v193, v185, v242
	v_add_u32_e32 v248, 0xc000, v213
	s_waitcnt lgkmcnt(2)
	v_mfma_f32_32x32x16_bf16 v[32:47], v[170:173], v[132:135], v[32:47]
	v_perm_b32 v186, v220, v186, v242
	v_perm_b32 v187, v221, v187, v242
	v_perm_b32 v188, v222, v188, v242
	v_perm_b32 v189, v223, v189, v242
	v_add_u32_e32 v249, 0xe000, v213
	s_waitcnt lgkmcnt(0)
	v_mfma_f32_32x32x16_bf16 v[32:47], v[178:181], v[136:139], v[32:47]
	global_store_dword v246, v182, s[80:81]
	global_store_dword v246, v183, s[80:81] offset:2048
	global_store_dword v247, v184, s[80:81]
	global_store_dword v247, v185, s[80:81] offset:2048
	v_mfma_f32_32x32x16_bf16 v[32:47], v[174:177], v[140:143], v[32:47]
	global_store_dword v248, v186, s[80:81]
	global_store_dword v248, v187, s[80:81] offset:2048
	global_store_dword v249, v188, s[80:81]
	global_store_dword v249, v189, s[80:81] offset:2048
	s_bitcmp1_b32 s29, 0
	s_cselect_b32 s34, 0xf400, 0
	s_add_i32 s30, s22, s29
	s_ashr_i32 s31, s30, 31
	s_lshl_b64 s[30:31], s[30:31], 14
	v_lshl_add_u64 v[240:241], v[214:215], 0, s[30:31]
	v_add_u32_e32 v194, s34, v235
	v_readlane_b32 s4, v164, s29
	s_add_i32 s29, s29, 1
	v_add_u32_e32 v165, v194, v236
	v_add_u32_e32 v194, v194, v244
	v_add_u32_e32 v195, v194, v236
	s_waitcnt lgkmcnt(0)
	s_barrier
	s_add_u32 s78, s78, 0x10000
	s_addc_u32 s79, s79, 0
	s_cmp_eq_u32 s78, 0x1f0000
	s_cbranch_scc0 .LBB0_379
	s_add_u32 s4, s17, s76
	s_addc_u32 s27, s20, s77
	s_lshl_b32 s28, s26, 8
	s_and_b32 s28, s28, 0x300
	s_add_u32 s4, s4, s28
	s_addc_u32 s27, s27, 0
	ds_read_b128 v[96:99], v237 offset:62464
	ds_read_b128 v[128:131], v237 offset:62496
	ds_read_b128 v[100:103], v238 offset:8704
	ds_read_b128 v[132:135], v238 offset:8736
	ds_read_b128 v[104:107], v238 offset:17408
	ds_read_b128 v[136:139], v238 offset:17440
	ds_read_b128 v[108:111], v238 offset:26112
	ds_read_b128 v[140:143], v238 offset:26144
	v_cvt_pk_bf16_f32 v80, v80, v81
	v_cvt_pk_bf16_f32 v81, v82, v83
	v_cvt_pk_bf16_f32 v82, v84, v85
	v_cvt_pk_bf16_f32 v83, v86, v87
	s_waitcnt vmcnt(16)
	v_and_b32_e32 v31, 0xffff0000, v15
	v_lshlrev_b32_e32 v30, 16, v15
	v_and_b32_e32 v29, 0xffff0000, v14
	v_lshlrev_b32_e32 v28, 16, v14
	v_and_b32_e32 v27, 0xffff0000, v13
	v_lshlrev_b32_e32 v26, 16, v13
	v_and_b32_e32 v25, 0xffff0000, v12
	v_lshlrev_b32_e32 v24, 16, v12
	v_and_b32_e32 v23, 0xffff0000, v11
	v_lshlrev_b32_e32 v22, 16, v11
	v_and_b32_e32 v21, 0xffff0000, v10
	v_lshlrev_b32_e32 v20, 16, v10
	v_and_b32_e32 v19, 0xffff0000, v9
	v_lshlrev_b32_e32 v18, 16, v9
	v_and_b32_e32 v17, 0xffff0000, v8
	v_lshlrev_b32_e32 v16, 16, v8
	v_and_b32_e32 v15, 0xffff0000, v7
	v_lshlrev_b32_e32 v14, 16, v7
	v_and_b32_e32 v13, 0xffff0000, v6
	v_lshlrev_b32_e32 v12, 16, v6
	v_and_b32_e32 v11, 0xffff0000, v5
	v_lshlrev_b32_e32 v10, 16, v5
	v_and_b32_e32 v9, 0xffff0000, v4
	v_lshlrev_b32_e32 v8, 16, v4
	v_and_b32_e32 v7, 0xffff0000, v3
	v_lshlrev_b32_e32 v6, 16, v3
	v_and_b32_e32 v5, 0xffff0000, v2
	v_lshlrev_b32_e32 v4, 16, v2
	v_and_b32_e32 v3, 0xffff0000, v1
	v_lshlrev_b32_e32 v2, 16, v1
	v_and_b32_e32 v1, 0xffff0000, v0
	v_lshlrev_b32_e32 v0, 16, v0
	s_waitcnt lgkmcnt(7)
	s_nop 0
	v_mfma_f32_32x32x16_bf16 v[0:15], v[96:99], v[80:83], v[0:15]
	s_waitcnt lgkmcnt(5)
	v_mfma_f32_32x32x16_bf16 v[16:31], v[100:103], v[80:83], v[16:31]
	s_waitcnt lgkmcnt(3)
	v_mfma_f32_32x32x16_bf16 v[112:127], v[104:107], v[80:83], 0
	s_waitcnt lgkmcnt(1)
	v_mfma_f32_32x32x16_bf16 v[96:111], v[108:111], v[80:83], 0
	ds_read_b128 v[80:83], v238 offset:26176
	ds_read_b128 v[84:87], v238 offset:17472
	ds_read_b128 v[144:147], v238 offset:8768
	ds_read_b128 v[148:151], v237 offset:62528
	v_cvt_pk_bf16_f32 v88, v88, v89
	v_cvt_pk_bf16_f32 v89, v90, v91
	v_cvt_pk_bf16_f32 v90, v92, v93
	v_cvt_pk_bf16_f32 v91, v94, v95
	s_nop 1
	v_mfma_f32_32x32x16_bf16 v[0:15], v[128:131], v[88:91], v[0:15]
	v_mfma_f32_32x32x16_bf16 v[16:31], v[132:135], v[88:91], v[16:31]
	v_mfma_f32_32x32x16_bf16 v[112:127], v[136:139], v[88:91], v[112:127]
	s_waitcnt lgkmcnt(4)
	v_mfma_f32_32x32x16_bf16 v[96:111], v[140:143], v[88:91], v[96:111]
	ds_read_b128 v[88:91], v237 offset:62560
	ds_read_b128 v[92:95], v238 offset:8800
	ds_read_b128 v[128:131], v238 offset:17504
	ds_read_b128 v[132:135], v238 offset:26208
	v_cvt_pk_bf16_f32 v64, v64, v65
	v_cvt_pk_bf16_f32 v65, v66, v67
	v_cvt_pk_bf16_f32 v66, v68, v69
	v_cvt_pk_bf16_f32 v67, v70, v71
	s_waitcnt lgkmcnt(4)
	s_nop 0
	v_mfma_f32_32x32x16_bf16 v[0:15], v[148:151], v[64:67], v[0:15]
	v_mfma_f32_32x32x16_bf16 v[16:31], v[144:147], v[64:67], v[16:31]
	v_mfma_f32_32x32x16_bf16 v[112:127], v[84:87], v[64:67], v[112:127]
	v_mfma_f32_32x32x16_bf16 v[96:111], v[80:83], v[64:67], v[96:111]
	ds_read_b128 v[64:67], v238 offset:26240
	ds_read_b128 v[68:71], v238 offset:17536
	ds_read_b128 v[80:83], v238 offset:8832
	ds_read_b128 v[84:87], v237 offset:62592
	v_cvt_pk_bf16_f32 v72, v72, v73
	v_cvt_pk_bf16_f32 v73, v74, v75
	v_cvt_pk_bf16_f32 v74, v76, v77
	v_cvt_pk_bf16_f32 v75, v78, v79
	s_waitcnt lgkmcnt(7)
	s_nop 0
	v_mfma_f32_32x32x16_bf16 v[0:15], v[88:91], v[72:75], v[0:15]
	s_waitcnt lgkmcnt(6)
	v_mfma_f32_32x32x16_bf16 v[16:31], v[92:95], v[72:75], v[16:31]
	s_waitcnt lgkmcnt(5)
	v_mfma_f32_32x32x16_bf16 v[112:127], v[128:131], v[72:75], v[112:127]
	s_waitcnt lgkmcnt(4)
	v_mfma_f32_32x32x16_bf16 v[96:111], v[132:135], v[72:75], v[96:111]
	ds_read_b128 v[72:75], v237 offset:62624
	ds_read_b128 v[76:79], v238 offset:8864
	ds_read_b128 v[88:91], v238 offset:17568
	ds_read_b128 v[92:95], v238 offset:26272
	v_cvt_pk_bf16_f32 v48, v48, v49
	v_cvt_pk_bf16_f32 v49, v50, v51
	v_cvt_pk_bf16_f32 v50, v52, v53
	v_cvt_pk_bf16_f32 v51, v54, v55
	s_waitcnt lgkmcnt(4)
	s_nop 0
	v_mfma_f32_32x32x16_bf16 v[0:15], v[84:87], v[48:51], v[0:15]
	v_mfma_f32_32x32x16_bf16 v[16:31], v[80:83], v[48:51], v[16:31]
	v_mfma_f32_32x32x16_bf16 v[112:127], v[68:71], v[48:51], v[112:127]
	v_mfma_f32_32x32x16_bf16 v[96:111], v[64:67], v[48:51], v[96:111]
	ds_read_b128 v[48:51], v238 offset:26304
	ds_read_b128 v[52:55], v238 offset:17600
	ds_read_b128 v[64:67], v238 offset:8896
	ds_read_b128 v[68:71], v237 offset:62656
	v_cvt_pk_bf16_f32 v56, v56, v57
	v_cvt_pk_bf16_f32 v57, v58, v59
	v_cvt_pk_bf16_f32 v58, v60, v61
	v_cvt_pk_bf16_f32 v59, v62, v63
	s_waitcnt lgkmcnt(7)
	s_nop 0
	v_mfma_f32_32x32x16_bf16 v[0:15], v[72:75], v[56:59], v[0:15]
	s_waitcnt lgkmcnt(6)
	v_mfma_f32_32x32x16_bf16 v[16:31], v[76:79], v[56:59], v[16:31]
	s_waitcnt lgkmcnt(5)
	v_mfma_f32_32x32x16_bf16 v[112:127], v[88:91], v[56:59], v[112:127]
	s_waitcnt lgkmcnt(4)
	v_mfma_f32_32x32x16_bf16 v[96:111], v[92:95], v[56:59], v[96:111]
	ds_read_b128 v[56:59], v237 offset:62688
	ds_read_b128 v[60:63], v238 offset:8928
	ds_read_b128 v[72:75], v238 offset:17632
	ds_read_b128 v[76:79], v238 offset:26336
	v_cvt_pk_bf16_f32 v32, v32, v33
	v_cvt_pk_bf16_f32 v33, v34, v35
	v_cvt_pk_bf16_f32 v34, v36, v37
	v_cvt_pk_bf16_f32 v35, v38, v39
	s_waitcnt lgkmcnt(4)
	s_nop 0
	v_mfma_f32_32x32x16_bf16 v[0:15], v[68:71], v[32:35], v[0:15]
	v_mfma_f32_32x32x16_bf16 v[16:31], v[64:67], v[32:35], v[16:31]
	v_mfma_f32_32x32x16_bf16 v[112:127], v[52:55], v[32:35], v[112:127]
	v_mfma_f32_32x32x16_bf16 v[96:111], v[48:51], v[32:35], v[96:111]
	ds_read_b128 v[32:35], v239 offset:4704
	ds_read_b128 v[36:39], v239 offset:4672
	ds_read_b128 v[48:51], v239 offset:4640
	ds_read_b128 v[52:55], v239 offset:4608
	ds_read_b128 v[64:67], v239
	ds_read_b128 v[68:71], v239 offset:32
	v_cvt_pk_bf16_f32 v40, v40, v41
	v_cvt_pk_bf16_f32 v41, v42, v43
	v_cvt_pk_bf16_f32 v42, v44, v45
	v_cvt_pk_bf16_f32 v43, v46, v47
	s_waitcnt lgkmcnt(9)
	s_nop 0
	v_mfma_f32_32x32x16_bf16 v[0:15], v[56:59], v[40:43], v[0:15]
	s_waitcnt lgkmcnt(8)
	v_mfma_f32_32x32x16_bf16 v[16:31], v[60:63], v[40:43], v[16:31]
	s_waitcnt lgkmcnt(7)
	v_mfma_f32_32x32x16_bf16 v[112:127], v[72:75], v[40:43], v[112:127]
	s_waitcnt lgkmcnt(6)
	v_mfma_f32_32x32x16_bf16 v[96:111], v[76:79], v[40:43], v[96:111]
	s_nop 5
	v_cvt_pk_bf16_f32 v0, v0, v1
	v_cvt_pk_bf16_f32 v1, v2, v3
	v_cvt_pk_bf16_f32 v2, v4, v5
	v_cvt_pk_bf16_f32 v3, v6, v7
	v_cvt_pk_bf16_f32 v4, v8, v9
	v_cvt_pk_bf16_f32 v5, v10, v11
	v_cvt_pk_bf16_f32 v6, v12, v13
	v_cvt_pk_bf16_f32 v7, v14, v15
	v_cvt_pk_bf16_f32 v8, v16, v17
	v_cvt_pk_bf16_f32 v9, v18, v19
	v_cvt_pk_bf16_f32 v10, v20, v21
	v_cvt_pk_bf16_f32 v11, v22, v23
	v_cvt_pk_bf16_f32 v12, v24, v25
	v_cvt_pk_bf16_f32 v13, v26, v27
	v_cvt_pk_bf16_f32 v14, v28, v29
	v_cvt_pk_bf16_f32 v15, v30, v31
	s_waitcnt lgkmcnt(2)
	v_mfma_f32_32x32x16_bf16 v[96:111], v[52:55], v[0:3], v[96:111]
	v_mfma_f32_32x32x16_bf16 v[96:111], v[48:51], v[4:7], v[96:111]
	s_waitcnt lgkmcnt(1)
	v_mfma_f32_32x32x16_bf16 v[112:127], v[64:67], v[0:3], v[112:127]
	v_mfma_f32_32x32x16_bf16 v[96:111], v[36:39], v[8:11], v[96:111]
	s_waitcnt lgkmcnt(0)
	v_mfma_f32_32x32x16_bf16 v[112:127], v[68:71], v[4:7], v[112:127]
	v_mfma_f32_32x32x16_bf16 v[96:111], v[32:35], v[12:15], v[96:111]
	v_mov_b32_e32 v1, v197
	v_mov_b32_e32 v2, v197
	s_add_u32 s76, s4, 0x1f0000
	s_nop 7
	v_mov_b32_dpp v1, v112 quad_perm:[1,0,3,2] row_mask:0xf bank_mask:0xf
	v_mov_b32_e32 v0, v213
	v_mov_b32_dpp v2, v113 quad_perm:[1,0,3,2] row_mask:0xf bank_mask:0xf
	v_cndmask_b32_e64 v1, v113, v1, s[40:41]
	s_addc_u32 s77, s27, 0
	v_cndmask_b32_e64 v2, v2, v112, s[40:41]
	v_cvt_pk_bf16_f32 v1, v2, v1
	global_store_dword v0, v1, s[76:77]
	v_mov_b32_e32 v1, v197
	v_mov_b32_e32 v2, v197
	s_nop 0
	v_mov_b32_dpp v1, v114 quad_perm:[1,0,3,2] row_mask:0xf bank_mask:0xf
	v_mov_b32_dpp v2, v115 quad_perm:[1,0,3,2] row_mask:0xf bank_mask:0xf
	v_cndmask_b32_e64 v2, v2, v114, s[40:41]
	v_cndmask_b32_e64 v1, v115, v1, s[40:41]
	v_cvt_pk_bf16_f32 v1, v2, v1
	v_add_u32_e32 v2, 0x800, v0
	global_store_dword v2, v1, s[76:77]
	v_mov_b32_e32 v1, v197
	v_mov_b32_e32 v2, v197
	s_nop 0
	v_mov_b32_dpp v1, v116 quad_perm:[1,0,3,2] row_mask:0xf bank_mask:0xf
	v_mov_b32_dpp v2, v117 quad_perm:[1,0,3,2] row_mask:0xf bank_mask:0xf
	v_cndmask_b32_e64 v2, v2, v116, s[40:41]
	v_cndmask_b32_e64 v1, v117, v1, s[40:41]
	v_cvt_pk_bf16_f32 v1, v2, v1
	v_add_u32_e32 v2, 0x2000, v0
	global_store_dword v2, v1, s[76:77]
	v_mov_b32_e32 v1, v197
	v_mov_b32_e32 v2, v197
	s_nop 0
	v_mov_b32_dpp v1, v118 quad_perm:[1,0,3,2] row_mask:0xf bank_mask:0xf
	v_mov_b32_dpp v2, v119 quad_perm:[1,0,3,2] row_mask:0xf bank_mask:0xf
	v_cndmask_b32_e64 v2, v2, v118, s[40:41]
	v_cndmask_b32_e64 v1, v119, v1, s[40:41]
	v_cvt_pk_bf16_f32 v1, v2, v1
	v_add_u32_e32 v2, 0x2800, v0
	global_store_dword v2, v1, s[76:77]
	v_mov_b32_e32 v1, v197
	v_mov_b32_e32 v2, v197
	s_nop 0
	v_mov_b32_dpp v1, v120 quad_perm:[1,0,3,2] row_mask:0xf bank_mask:0xf
	v_mov_b32_dpp v2, v121 quad_perm:[1,0,3,2] row_mask:0xf bank_mask:0xf
	v_cndmask_b32_e64 v2, v2, v120, s[40:41]
	v_cndmask_b32_e64 v1, v121, v1, s[40:41]
	v_cvt_pk_bf16_f32 v1, v2, v1
	v_add_u32_e32 v2, 0x4000, v0
	global_store_dword v2, v1, s[76:77]
	v_mov_b32_e32 v1, v197
	v_mov_b32_e32 v2, v197
	s_nop 0
	v_mov_b32_dpp v1, v122 quad_perm:[1,0,3,2] row_mask:0xf bank_mask:0xf
	v_mov_b32_dpp v2, v123 quad_perm:[1,0,3,2] row_mask:0xf bank_mask:0xf
	v_cndmask_b32_e64 v2, v2, v122, s[40:41]
	v_cndmask_b32_e64 v1, v123, v1, s[40:41]
	v_cvt_pk_bf16_f32 v1, v2, v1
	v_add_u32_e32 v2, 0x4800, v0
	global_store_dword v2, v1, s[76:77]
	v_mov_b32_e32 v1, v197
	v_mov_b32_e32 v2, v197
	s_nop 0
	v_mov_b32_dpp v1, v124 quad_perm:[1,0,3,2] row_mask:0xf bank_mask:0xf
	v_mov_b32_dpp v2, v125 quad_perm:[1,0,3,2] row_mask:0xf bank_mask:0xf
	v_cndmask_b32_e64 v2, v2, v124, s[40:41]
	v_cndmask_b32_e64 v1, v125, v1, s[40:41]
	v_cvt_pk_bf16_f32 v1, v2, v1
	v_add_u32_e32 v2, 0x6000, v0
	global_store_dword v2, v1, s[76:77]
	v_mov_b32_e32 v1, v197
	v_mov_b32_e32 v2, v197
	s_nop 0
	v_mov_b32_dpp v1, v126 quad_perm:[1,0,3,2] row_mask:0xf bank_mask:0xf
	v_mov_b32_dpp v2, v127 quad_perm:[1,0,3,2] row_mask:0xf bank_mask:0xf
	v_cndmask_b32_e64 v2, v2, v126, s[40:41]
	v_cndmask_b32_e64 v1, v127, v1, s[40:41]
	v_cvt_pk_bf16_f32 v1, v2, v1
	v_add_u32_e32 v2, 0x6800, v0
	global_store_dword v2, v1, s[76:77]
	v_mov_b32_e32 v1, v197
	v_mov_b32_e32 v2, v197
	s_nop 0
	v_mov_b32_dpp v1, v96 quad_perm:[1,0,3,2] row_mask:0xf bank_mask:0xf
	v_mov_b32_dpp v2, v97 quad_perm:[1,0,3,2] row_mask:0xf bank_mask:0xf
	v_cndmask_b32_e64 v2, v2, v96, s[40:41]
	v_cndmask_b32_e64 v1, v97, v1, s[40:41]
	v_cvt_pk_bf16_f32 v1, v2, v1
	v_add_u32_e32 v2, 0x8000, v0
	global_store_dword v2, v1, s[76:77]
	v_mov_b32_e32 v1, v197
	v_mov_b32_e32 v2, v197
	s_nop 0
	v_mov_b32_dpp v1, v98 quad_perm:[1,0,3,2] row_mask:0xf bank_mask:0xf
	v_mov_b32_dpp v2, v99 quad_perm:[1,0,3,2] row_mask:0xf bank_mask:0xf
	v_cndmask_b32_e64 v2, v2, v98, s[40:41]
	v_cndmask_b32_e64 v1, v99, v1, s[40:41]
	v_cvt_pk_bf16_f32 v1, v2, v1
	v_add_u32_e32 v2, 0x8800, v0
	global_store_dword v2, v1, s[76:77]
	v_mov_b32_e32 v1, v197
	v_mov_b32_e32 v2, v197
	s_nop 0
	v_mov_b32_dpp v1, v100 quad_perm:[1,0,3,2] row_mask:0xf bank_mask:0xf
	v_mov_b32_dpp v2, v101 quad_perm:[1,0,3,2] row_mask:0xf bank_mask:0xf
	v_cndmask_b32_e64 v2, v2, v100, s[40:41]
	v_cndmask_b32_e64 v1, v101, v1, s[40:41]
	v_cvt_pk_bf16_f32 v1, v2, v1
	v_add_u32_e32 v2, 0xa000, v0
	global_store_dword v2, v1, s[76:77]
	v_mov_b32_e32 v1, v197
	v_mov_b32_e32 v2, v197
	s_nop 0
	v_mov_b32_dpp v1, v102 quad_perm:[1,0,3,2] row_mask:0xf bank_mask:0xf
	v_mov_b32_dpp v2, v103 quad_perm:[1,0,3,2] row_mask:0xf bank_mask:0xf
	v_cndmask_b32_e64 v2, v2, v102, s[40:41]
	v_cndmask_b32_e64 v1, v103, v1, s[40:41]
	v_cvt_pk_bf16_f32 v1, v2, v1
	v_add_u32_e32 v2, 0xa800, v0
	global_store_dword v2, v1, s[76:77]
	v_mov_b32_e32 v1, v197
	v_mov_b32_e32 v2, v197
	s_nop 0
	v_mov_b32_dpp v1, v104 quad_perm:[1,0,3,2] row_mask:0xf bank_mask:0xf
	v_mov_b32_dpp v2, v105 quad_perm:[1,0,3,2] row_mask:0xf bank_mask:0xf
	v_cndmask_b32_e64 v2, v2, v104, s[40:41]
	v_cndmask_b32_e64 v1, v105, v1, s[40:41]
	v_cvt_pk_bf16_f32 v1, v2, v1
	v_add_u32_e32 v2, 0xc000, v0
	global_store_dword v2, v1, s[76:77]
	v_mov_b32_e32 v1, v197
	v_mov_b32_e32 v2, v197
	s_nop 0
	v_mov_b32_dpp v1, v106 quad_perm:[1,0,3,2] row_mask:0xf bank_mask:0xf
	v_mov_b32_dpp v2, v107 quad_perm:[1,0,3,2] row_mask:0xf bank_mask:0xf
	v_cndmask_b32_e64 v2, v2, v106, s[40:41]
	v_cndmask_b32_e64 v1, v107, v1, s[40:41]
	v_cvt_pk_bf16_f32 v1, v2, v1
	v_add_u32_e32 v2, 0xc800, v0
	global_store_dword v2, v1, s[76:77]
	v_mov_b32_e32 v1, v197
	v_mov_b32_e32 v2, v197
	s_nop 0
	v_mov_b32_dpp v1, v108 quad_perm:[1,0,3,2] row_mask:0xf bank_mask:0xf
	v_mov_b32_dpp v2, v109 quad_perm:[1,0,3,2] row_mask:0xf bank_mask:0xf
	v_cndmask_b32_e64 v2, v2, v108, s[40:41]
	v_cndmask_b32_e64 v1, v109, v1, s[40:41]
	v_cvt_pk_bf16_f32 v1, v2, v1
	v_add_u32_e32 v2, 0xe000, v0
	global_store_dword v2, v1, s[76:77]
	v_mov_b32_e32 v1, v197
	v_mov_b32_e32 v2, v197
	v_add_u32_e32 v0, 0xe800, v0
	v_mov_b32_dpp v1, v110 quad_perm:[1,0,3,2] row_mask:0xf bank_mask:0xf
	v_mov_b32_dpp v2, v111 quad_perm:[1,0,3,2] row_mask:0xf bank_mask:0xf
	v_cndmask_b32_e64 v1, v111, v1, s[40:41]
	v_cndmask_b32_e64 v2, v2, v110, s[40:41]
	v_cvt_pk_bf16_f32 v1, v2, v1
	global_store_dword v0, v1, s[76:77]
	s_waitcnt lgkmcnt(0)
	s_barrier
	s_mov_b64 s[76:77], 0
	s_mov_b64 s[34:35], 0x800
